# MFMA order variant m,bj,n,k across the 32-MFMA super-phase (srcB pair held for 8 MFMAs) + SwiGLU epilogue rewrite
# speedup vs baseline: 1.0231x; 1.0231x over previous
.LBB0_32:
	s_add_u32 s28, s54, 0xfff80080
	s_addc_u32 s29, s55, -1
	s_add_i32 s30, 0, 0x10000
	s_cmp_eq_u32 s27, 28
	s_cselect_b32 s79, s13, s29
	s_cselect_b32 s78, s16, s28
	s_cselect_b32 s69, s9, s26
	s_cselect_b32 s68, s24, s25
	s_add_i32 s31, 0, 0x14000
	v_add_u32_e32 v142, s30, v184
	v_add_u32_e32 v172, s31, v184
	ds_read_b128 v[130:133], v142
	ds_read_b128 v[134:137], v142 offset:1024
	ds_read_b128 v[138:141], v142 offset:2048
	ds_read_b128 v[142:145], v142 offset:3072
	ds_read_b128 v[146:149], v172
	ds_read_b128 v[150:153], v172 offset:1024
	ds_read_b128 v[154:157], v172 offset:2048
	ds_read_b128 v[172:175], v172 offset:3072
	v_lshl_add_u64 v[212:213], s[54:55], 0, v[166:167]
	s_add_i32 m0, s42, 0xc000
	ds_read_b128 v[176:179], v186
	ds_read_b128 v[180:183], v186 offset:1024
	ds_read_b128 v[188:191], v186 offset:2048
	ds_read_b128 v[192:195], v186 offset:3072
	ds_read_b128 v[196:199], v186 offset:4096
	ds_read_b128 v[200:203], v186 offset:5120
	ds_read_b128 v[204:207], v186 offset:6144
	ds_read_b128 v[208:211], v186 offset:7168
	global_load_lds_dwordx4 v[212:213], off
	v_lshl_add_u64 v[212:213], s[54:55], 0, v[168:169]
	s_add_i32 m0, s42, 0xe000
	s_nop 0
	global_load_lds_dwordx4 v[212:213], off
	s_waitcnt vmcnt(8)
	s_waitcnt lgkmcnt(0)
	s_barrier
	s_setprio 1
	s_waitcnt lgkmcnt(0)
	v_mfma_f32_16x16x32_bf16 v[126:129], v[130:133], v[176:179], v[126:129]
	v_mfma_f32_16x16x32_bf16 v[126:129], v[134:137], v[180:183], v[126:129]
	v_mfma_f32_16x16x32_bf16 v[122:125], v[138:141], v[176:179], v[122:125]
	v_mfma_f32_16x16x32_bf16 v[122:125], v[142:145], v[180:183], v[122:125]
	v_mfma_f32_16x16x32_bf16 v[118:121], v[146:149], v[176:179], v[118:121]
	v_mfma_f32_16x16x32_bf16 v[118:121], v[150:153], v[180:183], v[118:121]
	v_mfma_f32_16x16x32_bf16 v[114:117], v[154:157], v[176:179], v[114:117]
	v_mfma_f32_16x16x32_bf16 v[114:117], v[172:175], v[180:183], v[114:117]
	v_mfma_f32_16x16x32_bf16 v[110:113], v[130:133], v[188:191], v[110:113]
	v_mfma_f32_16x16x32_bf16 v[110:113], v[134:137], v[192:195], v[110:113]
	v_mfma_f32_16x16x32_bf16 v[106:109], v[138:141], v[188:191], v[106:109]
	v_mfma_f32_16x16x32_bf16 v[106:109], v[142:145], v[192:195], v[106:109]
	v_mfma_f32_16x16x32_bf16 v[102:105], v[146:149], v[188:191], v[102:105]
	v_mfma_f32_16x16x32_bf16 v[102:105], v[150:153], v[192:195], v[102:105]
	v_mfma_f32_16x16x32_bf16 v[98:101], v[154:157], v[188:191], v[98:101]
	v_mfma_f32_16x16x32_bf16 v[98:101], v[172:175], v[192:195], v[98:101]
	s_setprio 0
	s_setprio 1
	v_mfma_f32_16x16x32_bf16 v[94:97], v[130:133], v[196:199], v[94:97]
	v_mfma_f32_16x16x32_bf16 v[94:97], v[134:137], v[200:203], v[94:97]
	v_mfma_f32_16x16x32_bf16 v[90:93], v[138:141], v[196:199], v[90:93]
	v_mfma_f32_16x16x32_bf16 v[90:93], v[142:145], v[200:203], v[90:93]
	v_mfma_f32_16x16x32_bf16 v[86:89], v[146:149], v[196:199], v[86:89]
	v_mfma_f32_16x16x32_bf16 v[86:89], v[150:153], v[200:203], v[86:89]
	v_mfma_f32_16x16x32_bf16 v[82:85], v[154:157], v[196:199], v[82:85]
	v_mfma_f32_16x16x32_bf16 v[82:85], v[172:175], v[200:203], v[82:85]
	v_mfma_f32_16x16x32_bf16 v[78:81], v[130:133], v[204:207], v[78:81]
	v_mfma_f32_16x16x32_bf16 v[78:81], v[134:137], v[208:211], v[78:81]
	v_mfma_f32_16x16x32_bf16 v[74:77], v[138:141], v[204:207], v[74:77]
	v_mfma_f32_16x16x32_bf16 v[74:77], v[142:145], v[208:211], v[74:77]
	v_mfma_f32_16x16x32_bf16 v[70:73], v[146:149], v[204:207], v[70:73]
	v_mfma_f32_16x16x32_bf16 v[70:73], v[150:153], v[208:211], v[70:73]
	v_mfma_f32_16x16x32_bf16 v[66:69], v[154:157], v[204:207], v[66:69]
	v_mfma_f32_16x16x32_bf16 v[66:69], v[172:175], v[208:211], v[66:69]
	s_setprio 0
	s_barrier
	s_add_i32 s28, s30, s11
	v_lshl_add_u64 v[212:213], s[68:69], 0, v[160:161]
	s_mov_b32 m0, s28
	ds_read_b128 v[176:179], v186 offset:16384
	ds_read_b128 v[180:183], v186 offset:17408
	ds_read_b128 v[188:191], v186 offset:18432
	ds_read_b128 v[192:195], v186 offset:19456
	ds_read_b128 v[196:199], v186 offset:20480
	ds_read_b128 v[200:203], v186 offset:21504
	ds_read_b128 v[204:207], v186 offset:22528
	ds_read_b128 v[208:211], v186 offset:23552
	global_load_lds_dwordx4 v[212:213], off
	s_add_i32 m0, s28, 0x2000
	s_add_u32 s28, s68, 0x80000
	v_lshl_add_u64 v[232:233], s[68:69], 0, v[164:165]
	s_addc_u32 s29, s69, 0
	s_add_i32 s30, s31, s11
	global_load_lds_dwordx4 v[232:233], off
	v_lshl_add_u64 v[234:235], s[28:29], 0, v[160:161]
	s_mov_b32 m0, s30
	v_lshl_add_u64 v[236:237], s[78:79], 0, v[162:163]
	global_load_lds_dwordx4 v[234:235], off
	v_lshl_add_u64 v[234:235], s[28:29], 0, v[164:165]
	s_add_i32 m0, s30, 0x2000
	s_nop 0
	global_load_lds_dwordx4 v[234:235], off
	v_lshl_add_u64 v[234:235], s[78:79], 0, v[158:159]
	s_mov_b32 m0, s42
	s_nop 0
	global_load_lds_dwordx4 v[234:235], off
	s_mov_b32 m0, s57
	s_nop 0
	global_load_lds_dwordx4 v[236:237], off
	s_waitcnt vmcnt(8)
	s_waitcnt lgkmcnt(0)
	s_barrier
	s_setprio 1
	s_waitcnt lgkmcnt(0)
	v_mfma_f32_16x16x32_bf16 v[62:65], v[130:133], v[176:179], v[62:65]
	v_mfma_f32_16x16x32_bf16 v[62:65], v[134:137], v[180:183], v[62:65]
	v_mfma_f32_16x16x32_bf16 v[58:61], v[138:141], v[176:179], v[58:61]
	v_mfma_f32_16x16x32_bf16 v[58:61], v[142:145], v[180:183], v[58:61]
	v_mfma_f32_16x16x32_bf16 v[54:57], v[146:149], v[176:179], v[54:57]
	v_mfma_f32_16x16x32_bf16 v[54:57], v[150:153], v[180:183], v[54:57]
	v_mfma_f32_16x16x32_bf16 v[50:53], v[154:157], v[176:179], v[50:53]
	v_mfma_f32_16x16x32_bf16 v[50:53], v[172:175], v[180:183], v[50:53]
	v_mfma_f32_16x16x32_bf16 v[46:49], v[130:133], v[188:191], v[46:49]
	v_mfma_f32_16x16x32_bf16 v[46:49], v[134:137], v[192:195], v[46:49]
	v_mfma_f32_16x16x32_bf16 v[42:45], v[138:141], v[188:191], v[42:45]
	v_mfma_f32_16x16x32_bf16 v[42:45], v[142:145], v[192:195], v[42:45]
	v_mfma_f32_16x16x32_bf16 v[38:41], v[146:149], v[188:191], v[38:41]
	v_mfma_f32_16x16x32_bf16 v[38:41], v[150:153], v[192:195], v[38:41]
	v_mfma_f32_16x16x32_bf16 v[34:37], v[154:157], v[188:191], v[34:37]
	v_mfma_f32_16x16x32_bf16 v[34:37], v[172:175], v[192:195], v[34:37]
	s_setprio 0
	s_setprio 1
	v_mfma_f32_16x16x32_bf16 v[30:33], v[130:133], v[196:199], v[30:33]
	v_mfma_f32_16x16x32_bf16 v[30:33], v[134:137], v[200:203], v[30:33]
	v_mfma_f32_16x16x32_bf16 v[26:29], v[138:141], v[196:199], v[26:29]
	v_mfma_f32_16x16x32_bf16 v[26:29], v[142:145], v[200:203], v[26:29]
	v_mfma_f32_16x16x32_bf16 v[22:25], v[146:149], v[196:199], v[22:25]
	v_mfma_f32_16x16x32_bf16 v[22:25], v[150:153], v[200:203], v[22:25]
	v_mfma_f32_16x16x32_bf16 v[18:21], v[154:157], v[196:199], v[18:21]
	v_mfma_f32_16x16x32_bf16 v[18:21], v[172:175], v[200:203], v[18:21]
	v_mfma_f32_16x16x32_bf16 v[14:17], v[130:133], v[204:207], v[14:17]
	v_mfma_f32_16x16x32_bf16 v[14:17], v[134:137], v[208:211], v[14:17]
	v_mfma_f32_16x16x32_bf16 v[10:13], v[138:141], v[204:207], v[10:13]
	v_mfma_f32_16x16x32_bf16 v[10:13], v[142:145], v[208:211], v[10:13]
	v_mfma_f32_16x16x32_bf16 v[6:9], v[146:149], v[204:207], v[6:9]
	v_mfma_f32_16x16x32_bf16 v[6:9], v[150:153], v[208:211], v[6:9]
	v_mfma_f32_16x16x32_bf16 v[2:5], v[154:157], v[204:207], v[2:5]
	v_mfma_f32_16x16x32_bf16 v[2:5], v[172:175], v[208:211], v[2:5]
	s_setprio 0
	s_barrier
	s_add_i32 s30, 0, 0x18000
	s_add_i32 s31, 0, 0x1c000
	v_add_u32_e32 v142, s30, v184
	v_add_u32_e32 v172, s31, v184
	ds_read_b128 v[130:133], v142
	ds_read_b128 v[134:137], v142 offset:1024
	ds_read_b128 v[138:141], v142 offset:2048
	ds_read_b128 v[142:145], v142 offset:3072
	ds_read_b128 v[146:149], v172
	ds_read_b128 v[150:153], v172 offset:1024
	ds_read_b128 v[154:157], v172 offset:2048
	ds_read_b128 v[172:175], v172 offset:3072
	s_add_u32 s28, s78, 0x80000
	s_addc_u32 s29, s79, 0
	s_mov_b32 m0, s67
	v_lshl_add_u64 v[238:239], s[28:29], 0, v[158:159]
	ds_read_b128 v[176:179], v186 offset:32768
	ds_read_b128 v[180:183], v186 offset:33792
	ds_read_b128 v[188:191], v186 offset:34816
	ds_read_b128 v[192:195], v186 offset:35840
	ds_read_b128 v[196:199], v186 offset:36864
	ds_read_b128 v[200:203], v186 offset:37888
	ds_read_b128 v[204:207], v186 offset:38912
	ds_read_b128 v[208:211], v186 offset:39936
	global_load_lds_dwordx4 v[238:239], off
	v_lshl_add_u64 v[238:239], s[28:29], 0, v[162:163]
	s_mov_b32 m0, s72
	s_nop 0
	global_load_lds_dwordx4 v[238:239], off
	s_waitcnt vmcnt(8)
	s_waitcnt lgkmcnt(0)
	s_barrier
	s_setprio 1
	s_waitcnt lgkmcnt(0)
	v_mfma_f32_16x16x32_bf16 v[126:129], v[130:133], v[176:179], v[126:129]
	v_mfma_f32_16x16x32_bf16 v[126:129], v[134:137], v[180:183], v[126:129]
	v_mfma_f32_16x16x32_bf16 v[122:125], v[138:141], v[176:179], v[122:125]
	v_mfma_f32_16x16x32_bf16 v[122:125], v[142:145], v[180:183], v[122:125]
	v_mfma_f32_16x16x32_bf16 v[118:121], v[146:149], v[176:179], v[118:121]
	v_mfma_f32_16x16x32_bf16 v[118:121], v[150:153], v[180:183], v[118:121]
	v_mfma_f32_16x16x32_bf16 v[114:117], v[154:157], v[176:179], v[114:117]
	v_mfma_f32_16x16x32_bf16 v[114:117], v[172:175], v[180:183], v[114:117]
	v_mfma_f32_16x16x32_bf16 v[110:113], v[130:133], v[188:191], v[110:113]
	v_mfma_f32_16x16x32_bf16 v[110:113], v[134:137], v[192:195], v[110:113]
	v_mfma_f32_16x16x32_bf16 v[106:109], v[138:141], v[188:191], v[106:109]
	v_mfma_f32_16x16x32_bf16 v[106:109], v[142:145], v[192:195], v[106:109]
	v_mfma_f32_16x16x32_bf16 v[102:105], v[146:149], v[188:191], v[102:105]
	v_mfma_f32_16x16x32_bf16 v[102:105], v[150:153], v[192:195], v[102:105]
	v_mfma_f32_16x16x32_bf16 v[98:101], v[154:157], v[188:191], v[98:101]
	v_mfma_f32_16x16x32_bf16 v[98:101], v[172:175], v[192:195], v[98:101]
	s_setprio 0
	s_setprio 1
	v_mfma_f32_16x16x32_bf16 v[94:97], v[130:133], v[196:199], v[94:97]
	v_mfma_f32_16x16x32_bf16 v[94:97], v[134:137], v[200:203], v[94:97]
	v_mfma_f32_16x16x32_bf16 v[90:93], v[138:141], v[196:199], v[90:93]
	v_mfma_f32_16x16x32_bf16 v[90:93], v[142:145], v[200:203], v[90:93]
	v_mfma_f32_16x16x32_bf16 v[86:89], v[146:149], v[196:199], v[86:89]
	v_mfma_f32_16x16x32_bf16 v[86:89], v[150:153], v[200:203], v[86:89]
	v_mfma_f32_16x16x32_bf16 v[82:85], v[154:157], v[196:199], v[82:85]
	v_mfma_f32_16x16x32_bf16 v[82:85], v[172:175], v[200:203], v[82:85]
	v_mfma_f32_16x16x32_bf16 v[78:81], v[130:133], v[204:207], v[78:81]
	v_mfma_f32_16x16x32_bf16 v[78:81], v[134:137], v[208:211], v[78:81]
	v_mfma_f32_16x16x32_bf16 v[74:77], v[138:141], v[204:207], v[74:77]
	v_mfma_f32_16x16x32_bf16 v[74:77], v[142:145], v[208:211], v[74:77]
	v_mfma_f32_16x16x32_bf16 v[70:73], v[146:149], v[204:207], v[70:73]
	v_mfma_f32_16x16x32_bf16 v[70:73], v[150:153], v[208:211], v[70:73]
	v_mfma_f32_16x16x32_bf16 v[66:69], v[154:157], v[204:207], v[66:69]
	v_mfma_f32_16x16x32_bf16 v[66:69], v[172:175], v[208:211], v[66:69]
	s_setprio 0
	s_barrier
	s_add_i32 s28, s30, s11
	v_lshl_add_u64 v[212:213], v[212:213], 0, s[62:63]
	s_mov_b32 m0, s28
	ds_read_b128 v[176:179], v186 offset:49152
	ds_read_b128 v[180:183], v186 offset:50176
	ds_read_b128 v[188:191], v186 offset:51200
	ds_read_b128 v[192:195], v186 offset:52224
	ds_read_b128 v[196:199], v186 offset:53248
	ds_read_b128 v[200:203], v186 offset:54272
	ds_read_b128 v[204:207], v186 offset:55296
	ds_read_b128 v[208:211], v186 offset:56320
	global_load_lds_dwordx4 v[212:213], off
	s_add_i32 m0, s28, 0x2000
	s_add_u32 s28, s68, 0x80080
	v_lshl_add_u64 v[212:213], v[232:233], 0, s[62:63]
	s_addc_u32 s29, s69, 0
	s_add_i32 s30, s31, s11
	global_load_lds_dwordx4 v[212:213], off
	v_lshl_add_u64 v[212:213], s[28:29], 0, v[160:161]
	s_mov_b32 m0, s30
	s_nop 0
	global_load_lds_dwordx4 v[212:213], off
	v_lshl_add_u64 v[212:213], s[28:29], 0, v[164:165]
	s_add_i32 m0, s30, 0x2000
	s_nop 0
	global_load_lds_dwordx4 v[212:213], off
	v_lshl_add_u64 v[212:213], v[234:235], 0, s[62:63]
	s_mov_b32 m0, s18
	s_nop 0
	global_load_lds_dwordx4 v[212:213], off
	v_lshl_add_u64 v[212:213], v[236:237], 0, s[62:63]
	s_mov_b32 m0, s19
	s_nop 0
	global_load_lds_dwordx4 v[212:213], off
	s_waitcnt vmcnt(8)
	s_waitcnt lgkmcnt(0)
	s_barrier
	s_setprio 1
	s_waitcnt lgkmcnt(0)
	v_mfma_f32_16x16x32_bf16 v[62:65], v[130:133], v[176:179], v[62:65]
	v_mfma_f32_16x16x32_bf16 v[62:65], v[134:137], v[180:183], v[62:65]
	v_mfma_f32_16x16x32_bf16 v[58:61], v[138:141], v[176:179], v[58:61]
	v_mfma_f32_16x16x32_bf16 v[58:61], v[142:145], v[180:183], v[58:61]
	v_mfma_f32_16x16x32_bf16 v[54:57], v[146:149], v[176:179], v[54:57]
	v_mfma_f32_16x16x32_bf16 v[54:57], v[150:153], v[180:183], v[54:57]
	v_mfma_f32_16x16x32_bf16 v[50:53], v[154:157], v[176:179], v[50:53]
	v_mfma_f32_16x16x32_bf16 v[50:53], v[172:175], v[180:183], v[50:53]
	v_mfma_f32_16x16x32_bf16 v[46:49], v[130:133], v[188:191], v[46:49]
	v_mfma_f32_16x16x32_bf16 v[46:49], v[134:137], v[192:195], v[46:49]
	v_mfma_f32_16x16x32_bf16 v[42:45], v[138:141], v[188:191], v[42:45]
	v_mfma_f32_16x16x32_bf16 v[42:45], v[142:145], v[192:195], v[42:45]
	v_mfma_f32_16x16x32_bf16 v[38:41], v[146:149], v[188:191], v[38:41]
	v_mfma_f32_16x16x32_bf16 v[38:41], v[150:153], v[192:195], v[38:41]
	v_mfma_f32_16x16x32_bf16 v[34:37], v[154:157], v[188:191], v[34:37]
	v_mfma_f32_16x16x32_bf16 v[34:37], v[172:175], v[192:195], v[34:37]
	s_setprio 0
	s_setprio 1
	v_mfma_f32_16x16x32_bf16 v[30:33], v[130:133], v[196:199], v[30:33]
	v_mfma_f32_16x16x32_bf16 v[30:33], v[134:137], v[200:203], v[30:33]
	v_mfma_f32_16x16x32_bf16 v[26:29], v[138:141], v[196:199], v[26:29]
	v_mfma_f32_16x16x32_bf16 v[26:29], v[142:145], v[200:203], v[26:29]
	v_mfma_f32_16x16x32_bf16 v[22:25], v[146:149], v[196:199], v[22:25]
	v_mfma_f32_16x16x32_bf16 v[22:25], v[150:153], v[200:203], v[22:25]
	v_mfma_f32_16x16x32_bf16 v[18:21], v[154:157], v[196:199], v[18:21]
	v_mfma_f32_16x16x32_bf16 v[18:21], v[172:175], v[200:203], v[18:21]
	v_mfma_f32_16x16x32_bf16 v[14:17], v[130:133], v[204:207], v[14:17]
	v_mfma_f32_16x16x32_bf16 v[14:17], v[134:137], v[208:211], v[14:17]
	v_mfma_f32_16x16x32_bf16 v[10:13], v[138:141], v[204:207], v[10:13]
	v_mfma_f32_16x16x32_bf16 v[10:13], v[142:145], v[208:211], v[10:13]
	v_mfma_f32_16x16x32_bf16 v[6:9], v[146:149], v[204:207], v[6:9]
	v_mfma_f32_16x16x32_bf16 v[6:9], v[150:153], v[208:211], v[6:9]
	v_mfma_f32_16x16x32_bf16 v[2:5], v[154:157], v[204:207], v[2:5]
	v_mfma_f32_16x16x32_bf16 v[2:5], v[172:175], v[208:211], v[2:5]
	s_setprio 0
	s_barrier
	s_add_i32 s27, s27, 2
	s_add_u32 s54, s54, 0x100
	s_addc_u32 s55, s55, 0
	s_add_u32 s25, s25, 0x100
	s_addc_u32 s26, s26, 0
	s_cmp_gt_u32 s27, 29
	s_cbranch_scc0 .LBB0_32
	s_and_b64 vcc, exec, s[2:3]
	s_cbranch_vccz .LBB0_35
	s_barrier

.LBB0_132:
	s_add_u32 s23, s48, 0xfff80080
	s_addc_u32 s24, s49, -1
	s_add_i32 s25, 0, 0x10000
	s_cmp_eq_u32 s22, 28
	s_cselect_b32 s69, s3, s24
	s_cselect_b32 s68, s18, s23
	s_cselect_b32 s51, s1, s21
	s_cselect_b32 s50, s19, s20
	s_add_i32 s23, 0, 0x14000
	v_add_u32_e32 v156, s25, v165
	v_add_u32_e32 v169, s23, v165
	ds_read_b128 v[144:147], v156
	ds_read_b128 v[148:151], v156 offset:1024
	ds_read_b128 v[152:155], v156 offset:2048
	ds_read_b128 v[156:159], v156 offset:3072
	ds_read_b128 v[160:163], v169
	ds_read_b128 v[170:173], v169 offset:1024
	ds_read_b128 v[174:177], v169 offset:2048
	ds_read_b128 v[178:181], v169 offset:3072
	v_lshl_add_u64 v[232:233], s[48:49], 0, v[140:141]
	s_add_i32 m0, s45, 0xc000
	ds_read_b128 v[182:185], v168
	ds_read_b128 v[186:189], v168 offset:1024
	ds_read_b128 v[190:193], v168 offset:2048
	ds_read_b128 v[194:197], v168 offset:3072
	ds_read_b128 v[198:201], v168 offset:4096
	ds_read_b128 v[202:205], v168 offset:5120
	ds_read_b128 v[206:209], v168 offset:6144
	ds_read_b128 v[210:213], v168 offset:7168
	global_load_lds_dwordx4 v[232:233], off
	v_lshl_add_u64 v[232:233], s[48:49], 0, v[142:143]
	s_add_i32 m0, s45, 0xe000
	s_nop 0
	global_load_lds_dwordx4 v[232:233], off
	s_waitcnt vmcnt(8)
	s_waitcnt lgkmcnt(0)
	s_barrier
	s_setprio 1
	s_waitcnt lgkmcnt(0)
	v_mfma_f32_16x16x32_bf16 v[126:129], v[144:147], v[182:185], v[126:129]
	v_mfma_f32_16x16x32_bf16 v[126:129], v[148:151], v[186:189], v[126:129]
	v_mfma_f32_16x16x32_bf16 v[122:125], v[152:155], v[182:185], v[122:125]
	v_mfma_f32_16x16x32_bf16 v[122:125], v[156:159], v[186:189], v[122:125]
	v_mfma_f32_16x16x32_bf16 v[118:121], v[160:163], v[182:185], v[118:121]
	v_mfma_f32_16x16x32_bf16 v[118:121], v[170:173], v[186:189], v[118:121]
	v_mfma_f32_16x16x32_bf16 v[114:117], v[174:177], v[182:185], v[114:117]
	v_mfma_f32_16x16x32_bf16 v[114:117], v[178:181], v[186:189], v[114:117]
	v_mfma_f32_16x16x32_bf16 v[110:113], v[144:147], v[190:193], v[110:113]
	v_mfma_f32_16x16x32_bf16 v[110:113], v[148:151], v[194:197], v[110:113]
	v_mfma_f32_16x16x32_bf16 v[106:109], v[152:155], v[190:193], v[106:109]
	v_mfma_f32_16x16x32_bf16 v[106:109], v[156:159], v[194:197], v[106:109]
	v_mfma_f32_16x16x32_bf16 v[98:101], v[160:163], v[190:193], v[98:101]
	v_mfma_f32_16x16x32_bf16 v[98:101], v[170:173], v[194:197], v[98:101]
	v_mfma_f32_16x16x32_bf16 v[90:93], v[174:177], v[190:193], v[90:93]
	v_mfma_f32_16x16x32_bf16 v[90:93], v[178:181], v[194:197], v[90:93]
	s_setprio 0
	s_setprio 1
	v_mfma_f32_16x16x32_bf16 v[102:105], v[144:147], v[198:201], v[102:105]
	v_mfma_f32_16x16x32_bf16 v[102:105], v[148:151], v[202:205], v[102:105]
	v_mfma_f32_16x16x32_bf16 v[94:97], v[152:155], v[198:201], v[94:97]
	v_mfma_f32_16x16x32_bf16 v[94:97], v[156:159], v[202:205], v[94:97]
	v_mfma_f32_16x16x32_bf16 v[82:85], v[160:163], v[198:201], v[82:85]
	v_mfma_f32_16x16x32_bf16 v[82:85], v[170:173], v[202:205], v[82:85]
	v_mfma_f32_16x16x32_bf16 v[74:77], v[174:177], v[198:201], v[74:77]
	v_mfma_f32_16x16x32_bf16 v[74:77], v[178:181], v[202:205], v[74:77]
	v_mfma_f32_16x16x32_bf16 v[86:89], v[144:147], v[206:209], v[86:89]
	v_mfma_f32_16x16x32_bf16 v[86:89], v[148:151], v[210:213], v[86:89]
	v_mfma_f32_16x16x32_bf16 v[78:81], v[152:155], v[206:209], v[78:81]
	v_mfma_f32_16x16x32_bf16 v[78:81], v[156:159], v[210:213], v[78:81]
	v_mfma_f32_16x16x32_bf16 v[70:73], v[160:163], v[206:209], v[70:73]
	v_mfma_f32_16x16x32_bf16 v[70:73], v[170:173], v[210:213], v[70:73]
	v_mfma_f32_16x16x32_bf16 v[66:69], v[174:177], v[206:209], v[66:69]
	v_mfma_f32_16x16x32_bf16 v[66:69], v[178:181], v[210:213], v[66:69]
	s_setprio 0
	s_barrier
	s_add_i32 s24, s25, s16
	v_lshl_add_u64 v[232:233], s[50:51], 0, v[132:133]
	s_mov_b32 m0, s24
	ds_read_b128 v[182:185], v168 offset:16384
	ds_read_b128 v[186:189], v168 offset:17408
	ds_read_b128 v[190:193], v168 offset:18432
	ds_read_b128 v[194:197], v168 offset:19456
	ds_read_b128 v[198:201], v168 offset:20480
	ds_read_b128 v[202:205], v168 offset:21504
	ds_read_b128 v[206:209], v168 offset:22528
	ds_read_b128 v[210:213], v168 offset:23552
	global_load_lds_dwordx4 v[232:233], off
	s_add_i32 m0, s24, 0x2000
	s_add_u32 s24, s50, 0x80000
	v_lshl_add_u64 v[234:235], s[50:51], 0, v[136:137]
	s_addc_u32 s25, s51, 0
	s_add_i32 s23, s23, s16
	global_load_lds_dwordx4 v[234:235], off
	v_lshl_add_u64 v[236:237], s[24:25], 0, v[132:133]
	s_mov_b32 m0, s23
	v_lshl_add_u64 v[238:239], s[68:69], 0, v[134:135]
	global_load_lds_dwordx4 v[236:237], off
	v_lshl_add_u64 v[236:237], s[24:25], 0, v[136:137]
	s_add_i32 m0, s23, 0x2000
	s_nop 0
	global_load_lds_dwordx4 v[236:237], off
	v_lshl_add_u64 v[236:237], s[68:69], 0, v[130:131]
	s_mov_b32 m0, s45
	s_nop 0
	global_load_lds_dwordx4 v[236:237], off
	s_mov_b32 m0, s57
	s_nop 0
	global_load_lds_dwordx4 v[238:239], off
	s_waitcnt vmcnt(8)
	s_waitcnt lgkmcnt(0)
	s_barrier
	s_setprio 1
	s_waitcnt lgkmcnt(0)
	v_mfma_f32_16x16x32_bf16 v[62:65], v[144:147], v[182:185], v[62:65]
	v_mfma_f32_16x16x32_bf16 v[62:65], v[148:151], v[186:189], v[62:65]
	v_mfma_f32_16x16x32_bf16 v[58:61], v[152:155], v[182:185], v[58:61]
	v_mfma_f32_16x16x32_bf16 v[58:61], v[156:159], v[186:189], v[58:61]
	v_mfma_f32_16x16x32_bf16 v[50:53], v[160:163], v[182:185], v[50:53]
	v_mfma_f32_16x16x32_bf16 v[50:53], v[170:173], v[186:189], v[50:53]
	v_mfma_f32_16x16x32_bf16 v[42:45], v[174:177], v[182:185], v[42:45]
	v_mfma_f32_16x16x32_bf16 v[42:45], v[178:181], v[186:189], v[42:45]
	v_mfma_f32_16x16x32_bf16 v[54:57], v[144:147], v[190:193], v[54:57]
	v_mfma_f32_16x16x32_bf16 v[54:57], v[148:151], v[194:197], v[54:57]
	v_mfma_f32_16x16x32_bf16 v[46:49], v[152:155], v[190:193], v[46:49]
	v_mfma_f32_16x16x32_bf16 v[46:49], v[156:159], v[194:197], v[46:49]
	v_mfma_f32_16x16x32_bf16 v[34:37], v[160:163], v[190:193], v[34:37]
	v_mfma_f32_16x16x32_bf16 v[34:37], v[170:173], v[194:197], v[34:37]
	v_mfma_f32_16x16x32_bf16 v[26:29], v[174:177], v[190:193], v[26:29]
	v_mfma_f32_16x16x32_bf16 v[26:29], v[178:181], v[194:197], v[26:29]
	s_setprio 0
	s_setprio 1
	v_mfma_f32_16x16x32_bf16 v[38:41], v[144:147], v[198:201], v[38:41]
	v_mfma_f32_16x16x32_bf16 v[38:41], v[148:151], v[202:205], v[38:41]
	v_mfma_f32_16x16x32_bf16 v[30:33], v[152:155], v[198:201], v[30:33]
	v_mfma_f32_16x16x32_bf16 v[30:33], v[156:159], v[202:205], v[30:33]
	v_mfma_f32_16x16x32_bf16 v[18:21], v[160:163], v[198:201], v[18:21]
	v_mfma_f32_16x16x32_bf16 v[18:21], v[170:173], v[202:205], v[18:21]
	v_mfma_f32_16x16x32_bf16 v[10:13], v[174:177], v[198:201], v[10:13]
	v_mfma_f32_16x16x32_bf16 v[10:13], v[178:181], v[202:205], v[10:13]
	v_mfma_f32_16x16x32_bf16 v[22:25], v[144:147], v[206:209], v[22:25]
	v_mfma_f32_16x16x32_bf16 v[22:25], v[148:151], v[210:213], v[22:25]
	v_mfma_f32_16x16x32_bf16 v[14:17], v[152:155], v[206:209], v[14:17]
	v_mfma_f32_16x16x32_bf16 v[14:17], v[156:159], v[210:213], v[14:17]
	v_mfma_f32_16x16x32_bf16 v[6:9], v[160:163], v[206:209], v[6:9]
	v_mfma_f32_16x16x32_bf16 v[6:9], v[170:173], v[210:213], v[6:9]
	v_mfma_f32_16x16x32_bf16 v[2:5], v[174:177], v[206:209], v[2:5]
	v_mfma_f32_16x16x32_bf16 v[2:5], v[178:181], v[210:213], v[2:5]
	s_setprio 0
	s_barrier
	s_add_i32 s23, 0, 0x18000
	s_add_i32 s26, 0, 0x1c000
	v_add_u32_e32 v156, s23, v165
	v_add_u32_e32 v169, s26, v165
	ds_read_b128 v[144:147], v156
	ds_read_b128 v[148:151], v156 offset:1024
	ds_read_b128 v[152:155], v156 offset:2048
	ds_read_b128 v[156:159], v156 offset:3072
	ds_read_b128 v[160:163], v169
	ds_read_b128 v[170:173], v169 offset:1024
	ds_read_b128 v[174:177], v169 offset:2048
	ds_read_b128 v[178:181], v169 offset:3072
	s_add_u32 s24, s68, 0x80000
	s_addc_u32 s25, s69, 0
	s_mov_b32 m0, s42
	v_lshl_add_u64 v[240:241], s[24:25], 0, v[130:131]
	ds_read_b128 v[182:185], v168 offset:32768
	ds_read_b128 v[186:189], v168 offset:33792
	ds_read_b128 v[190:193], v168 offset:34816
	ds_read_b128 v[194:197], v168 offset:35840
	ds_read_b128 v[198:201], v168 offset:36864
	ds_read_b128 v[202:205], v168 offset:37888
	ds_read_b128 v[206:209], v168 offset:38912
	ds_read_b128 v[210:213], v168 offset:39936
	global_load_lds_dwordx4 v[240:241], off
	v_lshl_add_u64 v[240:241], s[24:25], 0, v[134:135]
	s_mov_b32 m0, s6
	s_nop 0
	global_load_lds_dwordx4 v[240:241], off
	s_waitcnt vmcnt(8)
	s_waitcnt lgkmcnt(0)
	s_barrier
	s_setprio 1
	s_waitcnt lgkmcnt(0)
	v_mfma_f32_16x16x32_bf16 v[126:129], v[144:147], v[182:185], v[126:129]
	v_mfma_f32_16x16x32_bf16 v[126:129], v[148:151], v[186:189], v[126:129]
	v_mfma_f32_16x16x32_bf16 v[122:125], v[152:155], v[182:185], v[122:125]
	v_mfma_f32_16x16x32_bf16 v[122:125], v[156:159], v[186:189], v[122:125]
	v_mfma_f32_16x16x32_bf16 v[118:121], v[160:163], v[182:185], v[118:121]
	v_mfma_f32_16x16x32_bf16 v[118:121], v[170:173], v[186:189], v[118:121]
	v_mfma_f32_16x16x32_bf16 v[114:117], v[174:177], v[182:185], v[114:117]
	v_mfma_f32_16x16x32_bf16 v[114:117], v[178:181], v[186:189], v[114:117]
	v_mfma_f32_16x16x32_bf16 v[110:113], v[144:147], v[190:193], v[110:113]
	v_mfma_f32_16x16x32_bf16 v[110:113], v[148:151], v[194:197], v[110:113]
	v_mfma_f32_16x16x32_bf16 v[106:109], v[152:155], v[190:193], v[106:109]
	v_mfma_f32_16x16x32_bf16 v[106:109], v[156:159], v[194:197], v[106:109]
	v_mfma_f32_16x16x32_bf16 v[98:101], v[160:163], v[190:193], v[98:101]
	v_mfma_f32_16x16x32_bf16 v[98:101], v[170:173], v[194:197], v[98:101]
	v_mfma_f32_16x16x32_bf16 v[90:93], v[174:177], v[190:193], v[90:93]
	v_mfma_f32_16x16x32_bf16 v[90:93], v[178:181], v[194:197], v[90:93]
	s_setprio 0
	s_setprio 1
	v_mfma_f32_16x16x32_bf16 v[102:105], v[144:147], v[198:201], v[102:105]
	v_mfma_f32_16x16x32_bf16 v[102:105], v[148:151], v[202:205], v[102:105]
	v_mfma_f32_16x16x32_bf16 v[94:97], v[152:155], v[198:201], v[94:97]
	v_mfma_f32_16x16x32_bf16 v[94:97], v[156:159], v[202:205], v[94:97]
	v_mfma_f32_16x16x32_bf16 v[82:85], v[160:163], v[198:201], v[82:85]
	v_mfma_f32_16x16x32_bf16 v[82:85], v[170:173], v[202:205], v[82:85]
	v_mfma_f32_16x16x32_bf16 v[74:77], v[174:177], v[198:201], v[74:77]
	v_mfma_f32_16x16x32_bf16 v[74:77], v[178:181], v[202:205], v[74:77]
	v_mfma_f32_16x16x32_bf16 v[86:89], v[144:147], v[206:209], v[86:89]
	v_mfma_f32_16x16x32_bf16 v[86:89], v[148:151], v[210:213], v[86:89]
	v_mfma_f32_16x16x32_bf16 v[78:81], v[152:155], v[206:209], v[78:81]
	v_mfma_f32_16x16x32_bf16 v[78:81], v[156:159], v[210:213], v[78:81]
	v_mfma_f32_16x16x32_bf16 v[70:73], v[160:163], v[206:209], v[70:73]
	v_mfma_f32_16x16x32_bf16 v[70:73], v[170:173], v[210:213], v[70:73]
	v_mfma_f32_16x16x32_bf16 v[66:69], v[174:177], v[206:209], v[66:69]
	v_mfma_f32_16x16x32_bf16 v[66:69], v[178:181], v[210:213], v[66:69]
	s_setprio 0
	s_barrier
	s_add_i32 s23, s23, s16
	v_lshl_add_u64 v[232:233], v[232:233], 0, s[62:63]
	s_mov_b32 m0, s23
	ds_read_b128 v[182:185], v168 offset:49152
	ds_read_b128 v[186:189], v168 offset:50176
	ds_read_b128 v[190:193], v168 offset:51200
	ds_read_b128 v[194:197], v168 offset:52224
	ds_read_b128 v[198:201], v168 offset:53248
	ds_read_b128 v[202:205], v168 offset:54272
	ds_read_b128 v[206:209], v168 offset:55296
	ds_read_b128 v[210:213], v168 offset:56320
	global_load_lds_dwordx4 v[232:233], off
	s_add_i32 m0, s23, 0x2000
	s_add_u32 s24, s50, 0x80080
	v_lshl_add_u64 v[232:233], v[234:235], 0, s[62:63]
	s_addc_u32 s25, s51, 0
	s_add_i32 s23, s26, s16
	global_load_lds_dwordx4 v[232:233], off
	v_lshl_add_u64 v[232:233], s[24:25], 0, v[132:133]
	s_mov_b32 m0, s23
	s_nop 0
	global_load_lds_dwordx4 v[232:233], off
	v_lshl_add_u64 v[232:233], s[24:25], 0, v[136:137]
	s_add_i32 m0, s23, 0x2000
	s_nop 0
	global_load_lds_dwordx4 v[232:233], off
	v_lshl_add_u64 v[232:233], v[236:237], 0, s[62:63]
	s_mov_b32 m0, s76
	s_nop 0
	global_load_lds_dwordx4 v[232:233], off
	v_lshl_add_u64 v[232:233], v[238:239], 0, s[62:63]
	s_mov_b32 m0, s77
	s_nop 0
	global_load_lds_dwordx4 v[232:233], off
	s_waitcnt vmcnt(8)
	s_waitcnt lgkmcnt(0)
	s_barrier
	s_setprio 1
	s_waitcnt lgkmcnt(0)
	v_mfma_f32_16x16x32_bf16 v[62:65], v[144:147], v[182:185], v[62:65]
	v_mfma_f32_16x16x32_bf16 v[62:65], v[148:151], v[186:189], v[62:65]
	v_mfma_f32_16x16x32_bf16 v[58:61], v[152:155], v[182:185], v[58:61]
	v_mfma_f32_16x16x32_bf16 v[58:61], v[156:159], v[186:189], v[58:61]
	v_mfma_f32_16x16x32_bf16 v[50:53], v[160:163], v[182:185], v[50:53]
	v_mfma_f32_16x16x32_bf16 v[50:53], v[170:173], v[186:189], v[50:53]
	v_mfma_f32_16x16x32_bf16 v[42:45], v[174:177], v[182:185], v[42:45]
	v_mfma_f32_16x16x32_bf16 v[42:45], v[178:181], v[186:189], v[42:45]
	v_mfma_f32_16x16x32_bf16 v[54:57], v[144:147], v[190:193], v[54:57]
	v_mfma_f32_16x16x32_bf16 v[54:57], v[148:151], v[194:197], v[54:57]
	v_mfma_f32_16x16x32_bf16 v[46:49], v[152:155], v[190:193], v[46:49]
	v_mfma_f32_16x16x32_bf16 v[46:49], v[156:159], v[194:197], v[46:49]
	v_mfma_f32_16x16x32_bf16 v[34:37], v[160:163], v[190:193], v[34:37]
	v_mfma_f32_16x16x32_bf16 v[34:37], v[170:173], v[194:197], v[34:37]
	v_mfma_f32_16x16x32_bf16 v[26:29], v[174:177], v[190:193], v[26:29]
	v_mfma_f32_16x16x32_bf16 v[26:29], v[178:181], v[194:197], v[26:29]
	s_setprio 0
	s_setprio 1
	v_mfma_f32_16x16x32_bf16 v[38:41], v[144:147], v[198:201], v[38:41]
	v_mfma_f32_16x16x32_bf16 v[38:41], v[148:151], v[202:205], v[38:41]
	v_mfma_f32_16x16x32_bf16 v[30:33], v[152:155], v[198:201], v[30:33]
	v_mfma_f32_16x16x32_bf16 v[30:33], v[156:159], v[202:205], v[30:33]
	v_mfma_f32_16x16x32_bf16 v[18:21], v[160:163], v[198:201], v[18:21]
	v_mfma_f32_16x16x32_bf16 v[18:21], v[170:173], v[202:205], v[18:21]
	v_mfma_f32_16x16x32_bf16 v[10:13], v[174:177], v[198:201], v[10:13]
	v_mfma_f32_16x16x32_bf16 v[10:13], v[178:181], v[202:205], v[10:13]
	v_mfma_f32_16x16x32_bf16 v[22:25], v[144:147], v[206:209], v[22:25]
	v_mfma_f32_16x16x32_bf16 v[22:25], v[148:151], v[210:213], v[22:25]
	v_mfma_f32_16x16x32_bf16 v[14:17], v[152:155], v[206:209], v[14:17]
	v_mfma_f32_16x16x32_bf16 v[14:17], v[156:159], v[210:213], v[14:17]
	v_mfma_f32_16x16x32_bf16 v[6:9], v[160:163], v[206:209], v[6:9]
	v_mfma_f32_16x16x32_bf16 v[6:9], v[170:173], v[210:213], v[6:9]
	v_mfma_f32_16x16x32_bf16 v[2:5], v[174:177], v[206:209], v[2:5]
	v_mfma_f32_16x16x32_bf16 v[2:5], v[178:181], v[210:213], v[2:5]
	s_setprio 0
	s_barrier
	s_add_i32 s22, s22, 2
	s_add_u32 s48, s48, 0x100
	s_addc_u32 s49, s49, 0
	s_add_u32 s20, s20, 0x100
	s_addc_u32 s21, s21, 0
	s_cmp_gt_u32 s22, 29
	s_cbranch_scc0 .LBB0_132
	s_and_b64 vcc, exec, s[10:11]
	s_cbranch_vccz .LBB0_135
	s_barrier

.LBB0_238:
	s_add_u32 s10, s12, 0x100
	s_addc_u32 s11, s13, 0
	s_add_i32 s23, 0, 0x10000
	s_cmpk_eq_i32 s22, 0x52
	s_cselect_b32 vcc_hi, s47, s11
	s_cselect_b32 vcc_lo, s46, s10
	s_cselect_b32 s51, s49, s21
	s_cselect_b32 s50, s48, s20
	s_add_i32 s24, 0, 0x14000
	v_add_u32_e32 v142, s23, v194
	v_add_u32_e32 v158, s24, v194
	ds_read_b128 v[122:125], v142
	ds_read_b128 v[126:129], v142 offset:1024
	ds_read_b128 v[138:141], v142 offset:2048
	ds_read_b128 v[142:145], v142 offset:3072
	ds_read_b128 v[146:149], v158
	ds_read_b128 v[150:153], v158 offset:1024
	ds_read_b128 v[154:157], v158 offset:2048
	ds_read_b128 v[158:161], v158 offset:3072
	v_lshl_add_u64 v[212:213], s[12:13], 0, v[170:171]
	s_add_i32 m0, s57, 0xc000
	ds_read_b128 v[174:177], v198
	ds_read_b128 v[178:181], v198 offset:1024
	ds_read_b128 v[182:185], v198 offset:2048
	ds_read_b128 v[186:189], v198 offset:3072
	ds_read_b128 v[190:193], v198 offset:4096
	ds_read_b128 v[200:203], v198 offset:5120
	ds_read_b128 v[204:207], v198 offset:6144
	ds_read_b128 v[208:211], v198 offset:7168
	global_load_lds_dwordx4 v[212:213], off
	v_lshl_add_u64 v[212:213], s[12:13], 0, v[172:173]
	s_add_i32 m0, s57, 0xe000
	s_nop 0
	global_load_lds_dwordx4 v[212:213], off
	s_waitcnt vmcnt(8)
	s_waitcnt lgkmcnt(0)
	s_barrier
	s_setprio 1
	s_waitcnt lgkmcnt(0)
	v_mfma_f32_16x16x32_bf16 v[134:137], v[122:125], v[174:177], v[134:137]
	v_mfma_f32_16x16x32_bf16 v[134:137], v[126:129], v[178:181], v[134:137]
	v_mfma_f32_16x16x32_bf16 v[130:133], v[138:141], v[174:177], v[130:133]
	v_mfma_f32_16x16x32_bf16 v[130:133], v[142:145], v[178:181], v[130:133]
	v_mfma_f32_16x16x32_bf16 v[118:121], v[146:149], v[174:177], v[118:121]
	v_mfma_f32_16x16x32_bf16 v[118:121], v[150:153], v[178:181], v[118:121]
	v_mfma_f32_16x16x32_bf16 v[114:117], v[154:157], v[174:177], v[114:117]
	v_mfma_f32_16x16x32_bf16 v[114:117], v[158:161], v[178:181], v[114:117]
	v_mfma_f32_16x16x32_bf16 v[110:113], v[122:125], v[182:185], v[110:113]
	v_mfma_f32_16x16x32_bf16 v[110:113], v[126:129], v[186:189], v[110:113]
	v_mfma_f32_16x16x32_bf16 v[106:109], v[138:141], v[182:185], v[106:109]
	v_mfma_f32_16x16x32_bf16 v[106:109], v[142:145], v[186:189], v[106:109]
	v_mfma_f32_16x16x32_bf16 v[102:105], v[146:149], v[182:185], v[102:105]
	v_mfma_f32_16x16x32_bf16 v[102:105], v[150:153], v[186:189], v[102:105]
	v_mfma_f32_16x16x32_bf16 v[98:101], v[154:157], v[182:185], v[98:101]
	v_mfma_f32_16x16x32_bf16 v[98:101], v[158:161], v[186:189], v[98:101]
	s_setprio 0
	s_setprio 1
	v_mfma_f32_16x16x32_bf16 v[94:97], v[122:125], v[190:193], v[94:97]
	v_mfma_f32_16x16x32_bf16 v[94:97], v[126:129], v[200:203], v[94:97]
	v_mfma_f32_16x16x32_bf16 v[90:93], v[138:141], v[190:193], v[90:93]
	v_mfma_f32_16x16x32_bf16 v[90:93], v[142:145], v[200:203], v[90:93]
	v_mfma_f32_16x16x32_bf16 v[86:89], v[146:149], v[190:193], v[86:89]
	v_mfma_f32_16x16x32_bf16 v[86:89], v[150:153], v[200:203], v[86:89]
	v_mfma_f32_16x16x32_bf16 v[82:85], v[154:157], v[190:193], v[82:85]
	v_mfma_f32_16x16x32_bf16 v[82:85], v[158:161], v[200:203], v[82:85]
	v_mfma_f32_16x16x32_bf16 v[78:81], v[122:125], v[204:207], v[78:81]
	v_mfma_f32_16x16x32_bf16 v[78:81], v[126:129], v[208:211], v[78:81]
	v_mfma_f32_16x16x32_bf16 v[74:77], v[138:141], v[204:207], v[74:77]
	v_mfma_f32_16x16x32_bf16 v[74:77], v[142:145], v[208:211], v[74:77]
	v_mfma_f32_16x16x32_bf16 v[70:73], v[146:149], v[204:207], v[70:73]
	v_mfma_f32_16x16x32_bf16 v[70:73], v[150:153], v[208:211], v[70:73]
	v_mfma_f32_16x16x32_bf16 v[66:69], v[154:157], v[204:207], v[66:69]
	v_mfma_f32_16x16x32_bf16 v[66:69], v[158:161], v[208:211], v[66:69]
	s_setprio 0
	s_barrier
	s_add_i32 s12, s23, s42
	v_lshl_add_u64 v[212:213], s[50:51], 0, v[164:165]
	s_mov_b32 m0, s12
	ds_read_b128 v[174:177], v198 offset:16384
	ds_read_b128 v[178:181], v198 offset:17408
	ds_read_b128 v[182:185], v198 offset:18432
	ds_read_b128 v[186:189], v198 offset:19456
	ds_read_b128 v[190:193], v198 offset:20480
	ds_read_b128 v[200:203], v198 offset:21504
	ds_read_b128 v[204:207], v198 offset:22528
	ds_read_b128 v[208:211], v198 offset:23552
	global_load_lds_dwordx4 v[212:213], off
	s_add_i32 m0, s12, 0x2000
	s_add_u32 s12, s50, 0x158000
	v_lshl_add_u64 v[232:233], s[50:51], 0, v[168:169]
	s_addc_u32 s13, s51, 0
	s_add_i32 s23, s24, s42
	global_load_lds_dwordx4 v[232:233], off
	v_lshl_add_u64 v[234:235], s[12:13], 0, v[164:165]
	s_mov_b32 m0, s23
	v_lshl_add_u64 v[236:237], vcc, 0, v[166:167]
	global_load_lds_dwordx4 v[234:235], off
	v_lshl_add_u64 v[234:235], s[12:13], 0, v[168:169]
	s_add_i32 m0, s23, 0x2000
	s_nop 0
	global_load_lds_dwordx4 v[234:235], off
	v_lshl_add_u64 v[234:235], vcc, 0, v[162:163]
	s_mov_b32 m0, s57
	s_nop 0
	global_load_lds_dwordx4 v[234:235], off
	s_mov_b32 m0, s58
	s_nop 0
	global_load_lds_dwordx4 v[236:237], off
	s_waitcnt vmcnt(8)
	s_waitcnt lgkmcnt(0)
	s_barrier
	s_setprio 1
	s_waitcnt lgkmcnt(0)
	v_mfma_f32_16x16x32_bf16 v[62:65], v[122:125], v[174:177], v[62:65]
	v_mfma_f32_16x16x32_bf16 v[62:65], v[126:129], v[178:181], v[62:65]
	v_mfma_f32_16x16x32_bf16 v[58:61], v[138:141], v[174:177], v[58:61]
	v_mfma_f32_16x16x32_bf16 v[58:61], v[142:145], v[178:181], v[58:61]
	v_mfma_f32_16x16x32_bf16 v[54:57], v[146:149], v[174:177], v[54:57]
	v_mfma_f32_16x16x32_bf16 v[54:57], v[150:153], v[178:181], v[54:57]
	v_mfma_f32_16x16x32_bf16 v[50:53], v[154:157], v[174:177], v[50:53]
	v_mfma_f32_16x16x32_bf16 v[50:53], v[158:161], v[178:181], v[50:53]
	v_mfma_f32_16x16x32_bf16 v[46:49], v[122:125], v[182:185], v[46:49]
	v_mfma_f32_16x16x32_bf16 v[46:49], v[126:129], v[186:189], v[46:49]
	v_mfma_f32_16x16x32_bf16 v[42:45], v[138:141], v[182:185], v[42:45]
	v_mfma_f32_16x16x32_bf16 v[42:45], v[142:145], v[186:189], v[42:45]
	v_mfma_f32_16x16x32_bf16 v[38:41], v[146:149], v[182:185], v[38:41]
	v_mfma_f32_16x16x32_bf16 v[38:41], v[150:153], v[186:189], v[38:41]
	v_mfma_f32_16x16x32_bf16 v[34:37], v[154:157], v[182:185], v[34:37]
	v_mfma_f32_16x16x32_bf16 v[34:37], v[158:161], v[186:189], v[34:37]
	s_setprio 0
	s_setprio 1
	v_mfma_f32_16x16x32_bf16 v[30:33], v[122:125], v[190:193], v[30:33]
	v_mfma_f32_16x16x32_bf16 v[30:33], v[126:129], v[200:203], v[30:33]
	v_mfma_f32_16x16x32_bf16 v[26:29], v[138:141], v[190:193], v[26:29]
	v_mfma_f32_16x16x32_bf16 v[26:29], v[142:145], v[200:203], v[26:29]
	v_mfma_f32_16x16x32_bf16 v[22:25], v[146:149], v[190:193], v[22:25]
	v_mfma_f32_16x16x32_bf16 v[22:25], v[150:153], v[200:203], v[22:25]
	v_mfma_f32_16x16x32_bf16 v[18:21], v[154:157], v[190:193], v[18:21]
	v_mfma_f32_16x16x32_bf16 v[18:21], v[158:161], v[200:203], v[18:21]
	v_mfma_f32_16x16x32_bf16 v[14:17], v[122:125], v[204:207], v[14:17]
	v_mfma_f32_16x16x32_bf16 v[14:17], v[126:129], v[208:211], v[14:17]
	v_mfma_f32_16x16x32_bf16 v[10:13], v[138:141], v[204:207], v[10:13]
	v_mfma_f32_16x16x32_bf16 v[10:13], v[142:145], v[208:211], v[10:13]
	v_mfma_f32_16x16x32_bf16 v[6:9], v[146:149], v[204:207], v[6:9]
	v_mfma_f32_16x16x32_bf16 v[6:9], v[150:153], v[208:211], v[6:9]
	v_mfma_f32_16x16x32_bf16 v[2:5], v[154:157], v[204:207], v[2:5]
	v_mfma_f32_16x16x32_bf16 v[2:5], v[158:161], v[208:211], v[2:5]
	s_setprio 0
	s_barrier
	s_add_i32 s23, 0, 0x18000
	s_add_i32 s24, 0, 0x1c000
	v_add_u32_e32 v142, s23, v194
	v_add_u32_e32 v158, s24, v194
	ds_read_b128 v[122:125], v142
	ds_read_b128 v[126:129], v142 offset:1024
	ds_read_b128 v[138:141], v142 offset:2048
	ds_read_b128 v[142:145], v142 offset:3072
	ds_read_b128 v[146:149], v158
	ds_read_b128 v[150:153], v158 offset:1024
	ds_read_b128 v[154:157], v158 offset:2048
	ds_read_b128 v[158:161], v158 offset:3072
	s_add_u32 s12, vcc_lo, 0x158000
	s_addc_u32 s13, vcc_hi, 0
	s_mov_b32 m0, s67
	v_lshl_add_u64 v[238:239], s[12:13], 0, v[162:163]
	ds_read_b128 v[174:177], v198 offset:32768
	ds_read_b128 v[178:181], v198 offset:33792
	ds_read_b128 v[182:185], v198 offset:34816
	ds_read_b128 v[186:189], v198 offset:35840
	ds_read_b128 v[190:193], v198 offset:36864
	ds_read_b128 v[200:203], v198 offset:37888
	ds_read_b128 v[204:207], v198 offset:38912
	ds_read_b128 v[208:211], v198 offset:39936
	global_load_lds_dwordx4 v[238:239], off
	v_lshl_add_u64 v[238:239], s[12:13], 0, v[166:167]
	s_mov_b32 m0, s76
	s_nop 0
	global_load_lds_dwordx4 v[238:239], off
	s_waitcnt vmcnt(8)
	s_waitcnt lgkmcnt(0)
	s_barrier
	s_setprio 1
	s_waitcnt lgkmcnt(0)
	v_mfma_f32_16x16x32_bf16 v[134:137], v[122:125], v[174:177], v[134:137]
	v_mfma_f32_16x16x32_bf16 v[134:137], v[126:129], v[178:181], v[134:137]
	v_mfma_f32_16x16x32_bf16 v[130:133], v[138:141], v[174:177], v[130:133]
	v_mfma_f32_16x16x32_bf16 v[130:133], v[142:145], v[178:181], v[130:133]
	v_mfma_f32_16x16x32_bf16 v[118:121], v[146:149], v[174:177], v[118:121]
	v_mfma_f32_16x16x32_bf16 v[118:121], v[150:153], v[178:181], v[118:121]
	v_mfma_f32_16x16x32_bf16 v[114:117], v[154:157], v[174:177], v[114:117]
	v_mfma_f32_16x16x32_bf16 v[114:117], v[158:161], v[178:181], v[114:117]
	v_mfma_f32_16x16x32_bf16 v[110:113], v[122:125], v[182:185], v[110:113]
	v_mfma_f32_16x16x32_bf16 v[110:113], v[126:129], v[186:189], v[110:113]
	v_mfma_f32_16x16x32_bf16 v[106:109], v[138:141], v[182:185], v[106:109]
	v_mfma_f32_16x16x32_bf16 v[106:109], v[142:145], v[186:189], v[106:109]
	v_mfma_f32_16x16x32_bf16 v[102:105], v[146:149], v[182:185], v[102:105]
	v_mfma_f32_16x16x32_bf16 v[102:105], v[150:153], v[186:189], v[102:105]
	v_mfma_f32_16x16x32_bf16 v[98:101], v[154:157], v[182:185], v[98:101]
	v_mfma_f32_16x16x32_bf16 v[98:101], v[158:161], v[186:189], v[98:101]
	s_setprio 0
	s_setprio 1
	v_mfma_f32_16x16x32_bf16 v[94:97], v[122:125], v[190:193], v[94:97]
	v_mfma_f32_16x16x32_bf16 v[94:97], v[126:129], v[200:203], v[94:97]
	v_mfma_f32_16x16x32_bf16 v[90:93], v[138:141], v[190:193], v[90:93]
	v_mfma_f32_16x16x32_bf16 v[90:93], v[142:145], v[200:203], v[90:93]
	v_mfma_f32_16x16x32_bf16 v[86:89], v[146:149], v[190:193], v[86:89]
	v_mfma_f32_16x16x32_bf16 v[86:89], v[150:153], v[200:203], v[86:89]
	v_mfma_f32_16x16x32_bf16 v[82:85], v[154:157], v[190:193], v[82:85]
	v_mfma_f32_16x16x32_bf16 v[82:85], v[158:161], v[200:203], v[82:85]
	v_mfma_f32_16x16x32_bf16 v[78:81], v[122:125], v[204:207], v[78:81]
	v_mfma_f32_16x16x32_bf16 v[78:81], v[126:129], v[208:211], v[78:81]
	v_mfma_f32_16x16x32_bf16 v[74:77], v[138:141], v[204:207], v[74:77]
	v_mfma_f32_16x16x32_bf16 v[74:77], v[142:145], v[208:211], v[74:77]
	v_mfma_f32_16x16x32_bf16 v[70:73], v[146:149], v[204:207], v[70:73]
	v_mfma_f32_16x16x32_bf16 v[70:73], v[150:153], v[208:211], v[70:73]
	v_mfma_f32_16x16x32_bf16 v[66:69], v[154:157], v[204:207], v[66:69]
	v_mfma_f32_16x16x32_bf16 v[66:69], v[158:161], v[208:211], v[66:69]
	s_setprio 0
	s_barrier
	s_add_i32 s12, s23, s42
	v_lshl_add_u64 v[212:213], v[212:213], 0, s[62:63]
	s_mov_b32 m0, s12
	ds_read_b128 v[174:177], v198 offset:49152
	ds_read_b128 v[178:181], v198 offset:50176
	ds_read_b128 v[182:185], v198 offset:51200
	ds_read_b128 v[186:189], v198 offset:52224
	ds_read_b128 v[190:193], v198 offset:53248
	ds_read_b128 v[200:203], v198 offset:54272
	ds_read_b128 v[204:207], v198 offset:55296
	ds_read_b128 v[208:211], v198 offset:56320
	global_load_lds_dwordx4 v[212:213], off
	s_add_i32 m0, s12, 0x2000
	s_add_u32 s12, s50, 0x158080
	v_lshl_add_u64 v[212:213], v[232:233], 0, s[62:63]
	s_addc_u32 s13, s51, 0
	s_add_i32 s23, s24, s42
	global_load_lds_dwordx4 v[212:213], off
	v_lshl_add_u64 v[212:213], s[12:13], 0, v[164:165]
	s_mov_b32 m0, s23
	s_nop 0
	global_load_lds_dwordx4 v[212:213], off
	v_lshl_add_u64 v[212:213], s[12:13], 0, v[168:169]
	s_add_i32 m0, s23, 0x2000
	s_nop 0
	global_load_lds_dwordx4 v[212:213], off
	v_lshl_add_u64 v[212:213], v[234:235], 0, s[62:63]
	s_mov_b32 m0, s1
	s_nop 0
	global_load_lds_dwordx4 v[212:213], off
	v_lshl_add_u64 v[212:213], v[236:237], 0, s[62:63]
	s_mov_b32 m0, s52
	s_nop 0
	global_load_lds_dwordx4 v[212:213], off
	s_waitcnt vmcnt(8)
	s_waitcnt lgkmcnt(0)
	s_barrier
	s_setprio 1
	s_waitcnt lgkmcnt(0)
	v_mfma_f32_16x16x32_bf16 v[62:65], v[122:125], v[174:177], v[62:65]
	v_mfma_f32_16x16x32_bf16 v[62:65], v[126:129], v[178:181], v[62:65]
	v_mfma_f32_16x16x32_bf16 v[58:61], v[138:141], v[174:177], v[58:61]
	v_mfma_f32_16x16x32_bf16 v[58:61], v[142:145], v[178:181], v[58:61]
	v_mfma_f32_16x16x32_bf16 v[54:57], v[146:149], v[174:177], v[54:57]
	v_mfma_f32_16x16x32_bf16 v[54:57], v[150:153], v[178:181], v[54:57]
	v_mfma_f32_16x16x32_bf16 v[50:53], v[154:157], v[174:177], v[50:53]
	v_mfma_f32_16x16x32_bf16 v[50:53], v[158:161], v[178:181], v[50:53]
	v_mfma_f32_16x16x32_bf16 v[46:49], v[122:125], v[182:185], v[46:49]
	v_mfma_f32_16x16x32_bf16 v[46:49], v[126:129], v[186:189], v[46:49]
	v_mfma_f32_16x16x32_bf16 v[42:45], v[138:141], v[182:185], v[42:45]
	v_mfma_f32_16x16x32_bf16 v[42:45], v[142:145], v[186:189], v[42:45]
	v_mfma_f32_16x16x32_bf16 v[38:41], v[146:149], v[182:185], v[38:41]
	v_mfma_f32_16x16x32_bf16 v[38:41], v[150:153], v[186:189], v[38:41]
	v_mfma_f32_16x16x32_bf16 v[34:37], v[154:157], v[182:185], v[34:37]
	v_mfma_f32_16x16x32_bf16 v[34:37], v[158:161], v[186:189], v[34:37]
	s_setprio 0
	s_setprio 1
	v_mfma_f32_16x16x32_bf16 v[30:33], v[122:125], v[190:193], v[30:33]
	v_mfma_f32_16x16x32_bf16 v[30:33], v[126:129], v[200:203], v[30:33]
	v_mfma_f32_16x16x32_bf16 v[26:29], v[138:141], v[190:193], v[26:29]
	v_mfma_f32_16x16x32_bf16 v[26:29], v[142:145], v[200:203], v[26:29]
	v_mfma_f32_16x16x32_bf16 v[22:25], v[146:149], v[190:193], v[22:25]
	v_mfma_f32_16x16x32_bf16 v[22:25], v[150:153], v[200:203], v[22:25]
	v_mfma_f32_16x16x32_bf16 v[18:21], v[154:157], v[190:193], v[18:21]
	v_mfma_f32_16x16x32_bf16 v[18:21], v[158:161], v[200:203], v[18:21]
	v_mfma_f32_16x16x32_bf16 v[14:17], v[122:125], v[204:207], v[14:17]
	v_mfma_f32_16x16x32_bf16 v[14:17], v[126:129], v[208:211], v[14:17]
	v_mfma_f32_16x16x32_bf16 v[10:13], v[138:141], v[204:207], v[10:13]
	v_mfma_f32_16x16x32_bf16 v[10:13], v[142:145], v[208:211], v[10:13]
	v_mfma_f32_16x16x32_bf16 v[6:9], v[146:149], v[204:207], v[6:9]
	v_mfma_f32_16x16x32_bf16 v[6:9], v[150:153], v[208:211], v[6:9]
	v_mfma_f32_16x16x32_bf16 v[2:5], v[154:157], v[204:207], v[2:5]
	v_mfma_f32_16x16x32_bf16 v[2:5], v[158:161], v[208:211], v[2:5]
	s_setprio 0
	s_barrier
	s_add_i32 s22, s22, 2
	s_add_u32 s20, s20, 0x100
	s_addc_u32 s21, s21, 0
	s_cmpk_gt_u32 s22, 0x53
	s_mov_b64 s[12:13], s[10:11]
	s_cbranch_scc0 .LBB0_238
	s_and_b64 vcc, exec, s[2:3]
	s_cbranch_vccz .LBB0_241
	s_barrier

.LBB0_340:
	s_add_u32 s22, s46, 0xfff80080
	s_addc_u32 s23, s47, -1
	s_add_i32 s24, 0, 0x10000
	s_cmp_eq_u32 s21, 28
	s_cselect_b32 s51, s1, s23
	s_cselect_b32 s50, s13, s22
	v_add_u32_e32 v148, s24, v152
	s_cselect_b32 s49, s11, s20
	s_cselect_b32 s48, s18, s19
	s_add_i32 s25, 0, 0x14000
	ds_read_b128 v[144:147], v148
	ds_read_b128 v[156:159], v148 offset:1024
	ds_read_b128 v[160:163], v148 offset:2048
	ds_read_b128 v[164:167], v148 offset:3072
	v_add_u32_e32 v148, s25, v152
	ds_read_b128 v[168:171], v148
	ds_read_b128 v[172:175], v148 offset:1024
	ds_read_b128 v[176:179], v148 offset:2048
	ds_read_b128 v[180:183], v148 offset:3072
	v_lshl_add_u64 v[148:149], s[46:47], 0, v[140:141]
	s_add_i32 m0, s3, 0xc000
	ds_read_b128 v[184:187], v154
	ds_read_b128 v[188:191], v154 offset:1024
	ds_read_b128 v[192:195], v154 offset:2048
	ds_read_b128 v[196:199], v154 offset:3072
	ds_read_b128 v[200:203], v154 offset:4096
	ds_read_b128 v[204:207], v154 offset:5120
	ds_read_b128 v[208:211], v154 offset:6144
	ds_read_b128 v[232:235], v154 offset:7168
	global_load_lds_dwordx4 v[148:149], off
	v_lshl_add_u64 v[148:149], s[46:47], 0, v[142:143]
	s_add_i32 m0, s3, 0xe000
	s_nop 0
	global_load_lds_dwordx4 v[148:149], off
	s_waitcnt vmcnt(8)
	s_waitcnt lgkmcnt(0)
	s_barrier
	s_setprio 1
	s_waitcnt lgkmcnt(0)
	v_mfma_f32_16x16x32_bf16 v[126:129], v[144:147], v[184:187], v[126:129]
	v_mfma_f32_16x16x32_bf16 v[126:129], v[156:159], v[188:191], v[126:129]
	v_mfma_f32_16x16x32_bf16 v[122:125], v[160:163], v[184:187], v[122:125]
	v_mfma_f32_16x16x32_bf16 v[122:125], v[164:167], v[188:191], v[122:125]
	v_mfma_f32_16x16x32_bf16 v[118:121], v[168:171], v[184:187], v[118:121]
	v_mfma_f32_16x16x32_bf16 v[118:121], v[172:175], v[188:191], v[118:121]
	v_mfma_f32_16x16x32_bf16 v[114:117], v[176:179], v[184:187], v[114:117]
	v_mfma_f32_16x16x32_bf16 v[114:117], v[180:183], v[188:191], v[114:117]
	v_mfma_f32_16x16x32_bf16 v[110:113], v[144:147], v[192:195], v[110:113]
	v_mfma_f32_16x16x32_bf16 v[110:113], v[156:159], v[196:199], v[110:113]
	v_mfma_f32_16x16x32_bf16 v[106:109], v[160:163], v[192:195], v[106:109]
	v_mfma_f32_16x16x32_bf16 v[106:109], v[164:167], v[196:199], v[106:109]
	v_mfma_f32_16x16x32_bf16 v[102:105], v[168:171], v[192:195], v[102:105]
	v_mfma_f32_16x16x32_bf16 v[102:105], v[172:175], v[196:199], v[102:105]
	v_mfma_f32_16x16x32_bf16 v[98:101], v[176:179], v[192:195], v[98:101]
	v_mfma_f32_16x16x32_bf16 v[98:101], v[180:183], v[196:199], v[98:101]
	s_setprio 0
	s_setprio 1
	v_mfma_f32_16x16x32_bf16 v[94:97], v[144:147], v[200:203], v[94:97]
	v_mfma_f32_16x16x32_bf16 v[94:97], v[156:159], v[204:207], v[94:97]
	v_mfma_f32_16x16x32_bf16 v[90:93], v[160:163], v[200:203], v[90:93]
	v_mfma_f32_16x16x32_bf16 v[90:93], v[164:167], v[204:207], v[90:93]
	v_mfma_f32_16x16x32_bf16 v[86:89], v[168:171], v[200:203], v[86:89]
	v_mfma_f32_16x16x32_bf16 v[86:89], v[172:175], v[204:207], v[86:89]
	v_mfma_f32_16x16x32_bf16 v[82:85], v[176:179], v[200:203], v[82:85]
	v_mfma_f32_16x16x32_bf16 v[82:85], v[180:183], v[204:207], v[82:85]
	v_mfma_f32_16x16x32_bf16 v[78:81], v[144:147], v[208:211], v[78:81]
	v_mfma_f32_16x16x32_bf16 v[78:81], v[156:159], v[232:235], v[78:81]
	v_mfma_f32_16x16x32_bf16 v[74:77], v[160:163], v[208:211], v[74:77]
	v_mfma_f32_16x16x32_bf16 v[74:77], v[164:167], v[232:235], v[74:77]
	v_mfma_f32_16x16x32_bf16 v[70:73], v[168:171], v[208:211], v[70:73]
	v_mfma_f32_16x16x32_bf16 v[70:73], v[172:175], v[232:235], v[70:73]
	v_mfma_f32_16x16x32_bf16 v[66:69], v[176:179], v[208:211], v[66:69]
	v_mfma_f32_16x16x32_bf16 v[66:69], v[180:183], v[232:235], v[66:69]
	s_setprio 0
	s_barrier
	s_add_i32 s22, s24, s16
	v_lshl_add_u64 v[148:149], s[48:49], 0, v[134:135]
	s_mov_b32 m0, s22
	ds_read_b128 v[184:187], v154 offset:16384
	ds_read_b128 v[188:191], v154 offset:17408
	ds_read_b128 v[192:195], v154 offset:18432
	ds_read_b128 v[196:199], v154 offset:19456
	ds_read_b128 v[200:203], v154 offset:20480
	ds_read_b128 v[204:207], v154 offset:21504
	ds_read_b128 v[208:211], v154 offset:22528
	ds_read_b128 v[232:235], v154 offset:23552
	global_load_lds_dwordx4 v[148:149], off
	s_add_i32 m0, s22, 0x2000
	s_add_u32 s22, s48, 0x80000
	v_lshl_add_u64 v[212:213], s[48:49], 0, v[130:131]
	s_addc_u32 s23, s49, 0
	s_add_i32 s24, s25, s16
	global_load_lds_dwordx4 v[212:213], off
	v_lshl_add_u64 v[236:237], s[22:23], 0, v[134:135]
	s_mov_b32 m0, s24
	v_lshl_add_u64 v[238:239], s[50:51], 0, v[132:133]
	global_load_lds_dwordx4 v[236:237], off
	v_lshl_add_u64 v[236:237], s[22:23], 0, v[130:131]
	s_add_i32 m0, s24, 0x2000
	s_nop 0
	global_load_lds_dwordx4 v[236:237], off
	v_lshl_add_u64 v[236:237], s[50:51], 0, v[136:137]
	s_mov_b32 m0, s3
	s_nop 0
	global_load_lds_dwordx4 v[236:237], off
	s_mov_b32 m0, s55
	s_nop 0
	global_load_lds_dwordx4 v[238:239], off
	s_waitcnt vmcnt(8)
	s_waitcnt lgkmcnt(0)
	s_barrier
	s_setprio 1
	s_waitcnt lgkmcnt(0)
	v_mfma_f32_16x16x32_bf16 v[62:65], v[144:147], v[184:187], v[62:65]
	v_mfma_f32_16x16x32_bf16 v[62:65], v[156:159], v[188:191], v[62:65]
	v_mfma_f32_16x16x32_bf16 v[58:61], v[160:163], v[184:187], v[58:61]
	v_mfma_f32_16x16x32_bf16 v[58:61], v[164:167], v[188:191], v[58:61]
	v_mfma_f32_16x16x32_bf16 v[54:57], v[168:171], v[184:187], v[54:57]
	v_mfma_f32_16x16x32_bf16 v[54:57], v[172:175], v[188:191], v[54:57]
	v_mfma_f32_16x16x32_bf16 v[50:53], v[176:179], v[184:187], v[50:53]
	v_mfma_f32_16x16x32_bf16 v[50:53], v[180:183], v[188:191], v[50:53]
	v_mfma_f32_16x16x32_bf16 v[46:49], v[144:147], v[192:195], v[46:49]
	v_mfma_f32_16x16x32_bf16 v[46:49], v[156:159], v[196:199], v[46:49]
	v_mfma_f32_16x16x32_bf16 v[42:45], v[160:163], v[192:195], v[42:45]
	v_mfma_f32_16x16x32_bf16 v[42:45], v[164:167], v[196:199], v[42:45]
	v_mfma_f32_16x16x32_bf16 v[38:41], v[168:171], v[192:195], v[38:41]
	v_mfma_f32_16x16x32_bf16 v[38:41], v[172:175], v[196:199], v[38:41]
	v_mfma_f32_16x16x32_bf16 v[34:37], v[176:179], v[192:195], v[34:37]
	v_mfma_f32_16x16x32_bf16 v[34:37], v[180:183], v[196:199], v[34:37]
	s_setprio 0
	s_setprio 1
	v_mfma_f32_16x16x32_bf16 v[30:33], v[144:147], v[200:203], v[30:33]
	v_mfma_f32_16x16x32_bf16 v[30:33], v[156:159], v[204:207], v[30:33]
	v_mfma_f32_16x16x32_bf16 v[26:29], v[160:163], v[200:203], v[26:29]
	v_mfma_f32_16x16x32_bf16 v[26:29], v[164:167], v[204:207], v[26:29]
	v_mfma_f32_16x16x32_bf16 v[22:25], v[168:171], v[200:203], v[22:25]
	v_mfma_f32_16x16x32_bf16 v[22:25], v[172:175], v[204:207], v[22:25]
	v_mfma_f32_16x16x32_bf16 v[18:21], v[176:179], v[200:203], v[18:21]
	v_mfma_f32_16x16x32_bf16 v[18:21], v[180:183], v[204:207], v[18:21]
	v_mfma_f32_16x16x32_bf16 v[14:17], v[144:147], v[208:211], v[14:17]
	v_mfma_f32_16x16x32_bf16 v[14:17], v[156:159], v[232:235], v[14:17]
	v_mfma_f32_16x16x32_bf16 v[10:13], v[160:163], v[208:211], v[10:13]
	v_mfma_f32_16x16x32_bf16 v[10:13], v[164:167], v[232:235], v[10:13]
	v_mfma_f32_16x16x32_bf16 v[6:9], v[168:171], v[208:211], v[6:9]
	v_mfma_f32_16x16x32_bf16 v[6:9], v[172:175], v[232:235], v[6:9]
	v_mfma_f32_16x16x32_bf16 v[2:5], v[176:179], v[208:211], v[2:5]
	v_mfma_f32_16x16x32_bf16 v[2:5], v[180:183], v[232:235], v[2:5]
	s_setprio 0
	s_barrier
	s_add_i32 s24, 0, 0x18000
	v_add_u32_e32 v155, s24, v152
	s_add_i32 s25, 0, 0x1c000
	ds_read_b128 v[144:147], v155
	ds_read_b128 v[156:159], v155 offset:1024
	ds_read_b128 v[160:163], v155 offset:2048
	ds_read_b128 v[164:167], v155 offset:3072
	v_add_u32_e32 v155, s25, v152
	ds_read_b128 v[168:171], v155
	ds_read_b128 v[172:175], v155 offset:1024
	ds_read_b128 v[176:179], v155 offset:2048
	ds_read_b128 v[180:183], v155 offset:3072
	s_add_u32 s22, s50, 0x80000
	s_addc_u32 s23, s51, 0
	s_mov_b32 m0, s57
	v_lshl_add_u64 v[240:241], s[22:23], 0, v[136:137]
	ds_read_b128 v[184:187], v154 offset:32768
	ds_read_b128 v[188:191], v154 offset:33792
	ds_read_b128 v[192:195], v154 offset:34816
	ds_read_b128 v[196:199], v154 offset:35840
	ds_read_b128 v[200:203], v154 offset:36864
	ds_read_b128 v[204:207], v154 offset:37888
	ds_read_b128 v[208:211], v154 offset:38912
	ds_read_b128 v[232:235], v154 offset:39936
	global_load_lds_dwordx4 v[240:241], off
	v_lshl_add_u64 v[240:241], s[22:23], 0, v[132:133]
	s_mov_b32 m0, s68
	s_nop 0
	global_load_lds_dwordx4 v[240:241], off
	s_waitcnt vmcnt(8)
	s_waitcnt lgkmcnt(0)
	s_barrier
	s_setprio 1
	s_waitcnt lgkmcnt(0)
	v_mfma_f32_16x16x32_bf16 v[126:129], v[144:147], v[184:187], v[126:129]
	v_mfma_f32_16x16x32_bf16 v[126:129], v[156:159], v[188:191], v[126:129]
	v_mfma_f32_16x16x32_bf16 v[122:125], v[160:163], v[184:187], v[122:125]
	v_mfma_f32_16x16x32_bf16 v[122:125], v[164:167], v[188:191], v[122:125]
	v_mfma_f32_16x16x32_bf16 v[118:121], v[168:171], v[184:187], v[118:121]
	v_mfma_f32_16x16x32_bf16 v[118:121], v[172:175], v[188:191], v[118:121]
	v_mfma_f32_16x16x32_bf16 v[114:117], v[176:179], v[184:187], v[114:117]
	v_mfma_f32_16x16x32_bf16 v[114:117], v[180:183], v[188:191], v[114:117]
	v_mfma_f32_16x16x32_bf16 v[110:113], v[144:147], v[192:195], v[110:113]
	v_mfma_f32_16x16x32_bf16 v[110:113], v[156:159], v[196:199], v[110:113]
	v_mfma_f32_16x16x32_bf16 v[106:109], v[160:163], v[192:195], v[106:109]
	v_mfma_f32_16x16x32_bf16 v[106:109], v[164:167], v[196:199], v[106:109]
	v_mfma_f32_16x16x32_bf16 v[102:105], v[168:171], v[192:195], v[102:105]
	v_mfma_f32_16x16x32_bf16 v[102:105], v[172:175], v[196:199], v[102:105]
	v_mfma_f32_16x16x32_bf16 v[98:101], v[176:179], v[192:195], v[98:101]
	v_mfma_f32_16x16x32_bf16 v[98:101], v[180:183], v[196:199], v[98:101]
	s_setprio 0
	s_setprio 1
	v_mfma_f32_16x16x32_bf16 v[94:97], v[144:147], v[200:203], v[94:97]
	v_mfma_f32_16x16x32_bf16 v[94:97], v[156:159], v[204:207], v[94:97]
	v_mfma_f32_16x16x32_bf16 v[90:93], v[160:163], v[200:203], v[90:93]
	v_mfma_f32_16x16x32_bf16 v[90:93], v[164:167], v[204:207], v[90:93]
	v_mfma_f32_16x16x32_bf16 v[86:89], v[168:171], v[200:203], v[86:89]
	v_mfma_f32_16x16x32_bf16 v[86:89], v[172:175], v[204:207], v[86:89]
	v_mfma_f32_16x16x32_bf16 v[82:85], v[176:179], v[200:203], v[82:85]
	v_mfma_f32_16x16x32_bf16 v[82:85], v[180:183], v[204:207], v[82:85]
	v_mfma_f32_16x16x32_bf16 v[78:81], v[144:147], v[208:211], v[78:81]
	v_mfma_f32_16x16x32_bf16 v[78:81], v[156:159], v[232:235], v[78:81]
	v_mfma_f32_16x16x32_bf16 v[74:77], v[160:163], v[208:211], v[74:77]
	v_mfma_f32_16x16x32_bf16 v[74:77], v[164:167], v[232:235], v[74:77]
	v_mfma_f32_16x16x32_bf16 v[70:73], v[168:171], v[208:211], v[70:73]
	v_mfma_f32_16x16x32_bf16 v[70:73], v[172:175], v[232:235], v[70:73]
	v_mfma_f32_16x16x32_bf16 v[66:69], v[176:179], v[208:211], v[66:69]
	v_mfma_f32_16x16x32_bf16 v[66:69], v[180:183], v[232:235], v[66:69]
	s_setprio 0
	s_barrier
	s_add_i32 s22, s24, s16
	v_lshl_add_u64 v[148:149], v[148:149], 0, s[62:63]
	s_mov_b32 m0, s22
	ds_read_b128 v[184:187], v154 offset:49152
	ds_read_b128 v[188:191], v154 offset:50176
	ds_read_b128 v[192:195], v154 offset:51200
	ds_read_b128 v[196:199], v154 offset:52224
	ds_read_b128 v[200:203], v154 offset:53248
	ds_read_b128 v[204:207], v154 offset:54272
	ds_read_b128 v[208:211], v154 offset:55296
	ds_read_b128 v[232:235], v154 offset:56320
	global_load_lds_dwordx4 v[148:149], off
	s_add_i32 m0, s22, 0x2000
	s_add_u32 s22, s48, 0x80080
	v_lshl_add_u64 v[148:149], v[212:213], 0, s[62:63]
	s_addc_u32 s23, s49, 0
	s_add_i32 s24, s25, s16
	global_load_lds_dwordx4 v[148:149], off
	v_lshl_add_u64 v[148:149], s[22:23], 0, v[134:135]
	s_mov_b32 m0, s24
	s_nop 0
	global_load_lds_dwordx4 v[148:149], off
	v_lshl_add_u64 v[148:149], s[22:23], 0, v[130:131]
	s_add_i32 m0, s24, 0x2000
	s_nop 0
	global_load_lds_dwordx4 v[148:149], off
	v_lshl_add_u64 v[148:149], v[236:237], 0, s[62:63]
	s_mov_b32 m0, s69
	s_nop 0
	global_load_lds_dwordx4 v[148:149], off
	v_lshl_add_u64 v[148:149], v[238:239], 0, s[62:63]
	s_mov_b32 m0, s70
	s_nop 0
	global_load_lds_dwordx4 v[148:149], off
	s_waitcnt vmcnt(8)
	s_waitcnt lgkmcnt(0)
	s_barrier
	s_setprio 1
	s_waitcnt lgkmcnt(0)
	v_mfma_f32_16x16x32_bf16 v[62:65], v[144:147], v[184:187], v[62:65]
	v_mfma_f32_16x16x32_bf16 v[62:65], v[156:159], v[188:191], v[62:65]
	v_mfma_f32_16x16x32_bf16 v[58:61], v[160:163], v[184:187], v[58:61]
	v_mfma_f32_16x16x32_bf16 v[58:61], v[164:167], v[188:191], v[58:61]
	v_mfma_f32_16x16x32_bf16 v[54:57], v[168:171], v[184:187], v[54:57]
	v_mfma_f32_16x16x32_bf16 v[54:57], v[172:175], v[188:191], v[54:57]
	v_mfma_f32_16x16x32_bf16 v[50:53], v[176:179], v[184:187], v[50:53]
	v_mfma_f32_16x16x32_bf16 v[50:53], v[180:183], v[188:191], v[50:53]
	v_mfma_f32_16x16x32_bf16 v[46:49], v[144:147], v[192:195], v[46:49]
	v_mfma_f32_16x16x32_bf16 v[46:49], v[156:159], v[196:199], v[46:49]
	v_mfma_f32_16x16x32_bf16 v[42:45], v[160:163], v[192:195], v[42:45]
	v_mfma_f32_16x16x32_bf16 v[42:45], v[164:167], v[196:199], v[42:45]
	v_mfma_f32_16x16x32_bf16 v[38:41], v[168:171], v[192:195], v[38:41]
	v_mfma_f32_16x16x32_bf16 v[38:41], v[172:175], v[196:199], v[38:41]
	v_mfma_f32_16x16x32_bf16 v[34:37], v[176:179], v[192:195], v[34:37]
	v_mfma_f32_16x16x32_bf16 v[34:37], v[180:183], v[196:199], v[34:37]
	s_setprio 0
	s_setprio 1
	v_mfma_f32_16x16x32_bf16 v[30:33], v[144:147], v[200:203], v[30:33]
	v_mfma_f32_16x16x32_bf16 v[30:33], v[156:159], v[204:207], v[30:33]
	v_mfma_f32_16x16x32_bf16 v[26:29], v[160:163], v[200:203], v[26:29]
	v_mfma_f32_16x16x32_bf16 v[26:29], v[164:167], v[204:207], v[26:29]
	v_mfma_f32_16x16x32_bf16 v[22:25], v[168:171], v[200:203], v[22:25]
	v_mfma_f32_16x16x32_bf16 v[22:25], v[172:175], v[204:207], v[22:25]
	v_mfma_f32_16x16x32_bf16 v[18:21], v[176:179], v[200:203], v[18:21]
	v_mfma_f32_16x16x32_bf16 v[18:21], v[180:183], v[204:207], v[18:21]
	v_mfma_f32_16x16x32_bf16 v[14:17], v[144:147], v[208:211], v[14:17]
	v_mfma_f32_16x16x32_bf16 v[14:17], v[156:159], v[232:235], v[14:17]
	v_mfma_f32_16x16x32_bf16 v[10:13], v[160:163], v[208:211], v[10:13]
	v_mfma_f32_16x16x32_bf16 v[10:13], v[164:167], v[232:235], v[10:13]
	v_mfma_f32_16x16x32_bf16 v[6:9], v[168:171], v[208:211], v[6:9]
	v_mfma_f32_16x16x32_bf16 v[6:9], v[172:175], v[232:235], v[6:9]
	v_mfma_f32_16x16x32_bf16 v[2:5], v[176:179], v[208:211], v[2:5]
	v_mfma_f32_16x16x32_bf16 v[2:5], v[180:183], v[232:235], v[2:5]
	s_setprio 0
	s_barrier
	s_add_i32 s21, s21, 2
	s_add_u32 s46, s46, 0x100
	s_addc_u32 s47, s47, 0
	s_add_u32 s19, s19, 0x100
	s_addc_u32 s20, s20, 0
	s_cmp_gt_u32 s21, 29
	s_cbranch_scc0 .LBB0_340
	s_and_b64 vcc, exec, s[8:9]
	s_cbranch_vccz .LBB0_343
	s_barrier
